# plus static s_setprio 1 for waves 4-7 during the DA phase
# baseline (speedup 1.0000x reference)
.LBB0_276:
	s_cmp_gt_i32 s88, 3
	s_cselect_b64 s[0:1], -1, 0
	s_cmp_lt_i32 s89, 4
	s_cselect_b64 s[2:3], -1, 0
	s_or_b64 s[0:1], s[0:1], s[2:3]
	s_and_b64 vcc, exec, s[0:1]
	s_cbranch_vccnz .LBB0_356
	s_cmpk_gt_i32 s10, 0x8ff
	s_cbranch_scc1 .LBB0_304
	v_readlane_b32 s1, v239, 43
	s_nop 3
	s_cmpk_lt_u32 s1, 0x100
	s_cbranch_scc1 .Lprio_skip_da
	s_setprio 1
.Lprio_skip_da:
	v_mbcnt_lo_u32_b32 v0, -1, 0
	s_and_b32 s0, s1, 0xffffffc0
	s_bfe_u32 s11, s1, 0x10006
	v_mbcnt_hi_u32_b32 v166, -1, v0
	s_lshl_b32 s8, s11, 3
	v_lshrrev_b32_e32 v168, 5, v166
	v_add_u32_e32 v0, s0, v166
	v_ashrrev_i32_e32 v148, 4, v0
	v_lshlrev_b32_e32 v2, 3, v166
	v_ashrrev_i32_e32 v152, 3, v0
	v_add_u32_e32 v0, s8, v168
	s_lshr_b32 s6, s1, 7
	v_and_b32_e32 v172, 8, v2
	v_bitop3_b32 v2, v0, v166, 15 bitop3:0x78
	s_lshl_b32 s12, s6, 5
	s_and_b32 s4, 64, s1
	v_lshlrev_b32_e32 v174, 4, v2
	v_add_u32_e32 v2, 2, v0
	s_cmp_eq_u32 s11, 0
	v_bitop3_b32 v2, v2, v166, 15 bitop3:0x78
	s_cselect_b64 s[2:3], -1, 0
	s_cmp_lg_u32 s4, 0
	v_readlane_b32 s36, v239, 32
	v_and_b32_e32 v167, 31, v166
	v_xor_b32_e32 v4, v148, v166
	v_lshlrev_b32_e32 v175, 4, v2
	v_add_u32_e32 v2, 4, v0
	v_add_u32_e32 v0, 6, v0
	s_cselect_b64 s[4:5], -1, 0
	s_lshl_b32 s13, s6, 14
	s_add_i32 s22, s12, 0x100
	s_lshl_b32 s23, s11, 6
	v_readlane_b32 s40, v239, 36
	s_movk_i32 s9, 0xff90
	v_lshlrev_b32_e32 v4, 4, v4
	v_lshlrev_b32_e32 v173, 8, v167
	v_bitop3_b32 v2, v2, v166, 15 bitop3:0x78
	v_bitop3_b32 v0, v0, v166, 15 bitop3:0x78
	v_readlane_b32 s37, v239, 33
	v_readlane_b32 s38, v239, 34
	v_readlane_b32 s39, v239, 35
	v_readlane_b32 s41, v239, 37
	v_readlane_b32 s42, v239, 38
	v_readlane_b32 s43, v239, 39
	s_add_u32 s30, s40, 0x30000
	v_lshlrev_b32_e32 v146, 4, v168
	v_lshlrev_b32_e32 v3, 4, v166
	s_waitcnt lgkmcnt(1)
	v_and_b32_e32 v5, 7, v166
	v_lshlrev_b32_e32 v170, 8, v148
	v_and_b32_e32 v171, 0xf0, v4
	v_lshlrev_b32_e32 v176, 4, v2
	v_lshlrev_b32_e32 v177, 4, v0
	v_mad_i32_i24 v0, v167, s9, v173
	s_mov_b32 s1, 0
	s_addc_u32 s31, s41, 0
	s_lshl_b32 s33, s10, 8
	s_lshl_b32 s34, s14, 8
	v_mov_b32_e32 v1, 0
	s_movk_i32 s35, 0x1200
	s_mov_b32 s36, 0x10000
	s_movk_i32 s37, 0x90
	s_mov_b32 s38, 0x48000
	s_mov_b32 s39, 0x20000
	s_mov_b32 s40, 0x30000
	s_mov_b32 s41, 0xff800000
	s_mov_b32 s42, 0x40000
	s_mov_b32 s43, 0x50000
	v_mov_b32_e32 v145, 0xbfb8aa3b
	s_mov_b32 s44, 0x60000
	s_mov_b32 s45, 0x70000
	v_mov_b32_e32 v157, 0x358637bd
	s_mov_b32 s46, 0x800000
	s_mov_b32 s47, 0xffff0000
	s_mov_b64 s[6:7], 0x20000
	v_mov_b32_e32 v169, 0x900
	v_ashrrev_i32_e32 v149, 31, v148
	v_and_b32_e32 v150, 0xf0, v3
	v_ashrrev_i32_e32 v153, 31, v152
	v_lshlrev_b32_e32 v154, 4, v5
	v_and_b32_e32 v156, 0x60, v3
	v_or_b32_e32 v178, v170, v171
	v_add_u32_e32 v179, v173, v174
	v_add_u32_e32 v180, v173, v175
	v_add_u32_e32 v181, v173, v176
	v_add_u32_e32 v182, v173, v177
	v_mov_b32_e32 v183, 0xff800000
	v_add_u32_e32 v184, v0, v146
	v_mov_b32_e32 v185, 0x480000
	s_mov_b32 s48, s10
	s_branch .LBB0_281

.LBB0_304:
	s_setprio 0
	s_cmp_lt_i32 s89, 5
	s_cbranch_scc1 .LBB0_356
	s_waitcnt vmcnt(0)
	v_readlane_b32 s0, v239, 43
	s_cmp_gt_u32 s0, 63
	s_waitcnt lgkmcnt(0)
	s_barrier
	s_cbranch_scc1 .LBB0_355
	v_mbcnt_lo_u32_b32 v0, -1, 0
	v_mbcnt_hi_u32_b32 v0, -1, v0
	v_cmp_eq_u32_e32 vcc, 0, v0
	s_and_saveexec_b64 s[0:1], vcc
	s_cbranch_execz .LBB0_354
	v_mov_b32_e32 v0, 0x23000
	s_waitcnt vmcnt(0) expcnt(0) lgkmcnt(0)
	ds_read_b32 v2, v0
	v_mov_b32_e32 v0, 0x23004
	ds_read_b32 v0, v0
	s_waitcnt lgkmcnt(1)
	v_cmp_ne_u32_e32 vcc, 0, v2
	s_cbranch_vccnz .LBB0_322
	v_readlane_b32 s2, v239, 42
	s_mul_i32 s11, s15, s2
	s_add_u32 s2, s28, 0x1000
	s_addc_u32 s3, s29, 0
	s_add_u32 s4, s28, 0x1100
	s_addc_u32 s5, s29, 0
	s_add_u32 s6, s28, 0x1200
	s_addc_u32 s7, s29, 0
	s_add_u32 s8, s28, 0x1300
	s_mul_i32 s11, s11, s14
	s_addc_u32 s9, s29, 0
	s_mov_b32 s30, 1
	v_mov_b32_e32 v16, 0
	s_branch .LBB0_310
